# P1 per-head norm epilogue: all 8 gain loads issued together after the reduction (was 3 serialized load-wait steps)
# speedup vs baseline: 1.0035x; 1.0035x over previous
; DI void phase1(const Params& p, int l, char* lds) {
;     ...
;       if (gain != nullptr) {
; #pragma unroll
;         for (int mi = 0; mi < 2; ++mi) {
;           float ss = 0.f;
; #pragma unroll
;           for (int ni = 0; ni < 2; ++ni)
; #pragma unroll
;             for (int i = 0; i < 16; ++i) ss += acc[mi][ni][i] * acc[mi][ni][i];
;           ss += shx(ss, lane, 32);
.LBB0_230:
	s_or_b64 exec, exec, s[14:15]
	v_cmp_ne_u64_e32 vcc, 0, v[66:67]
	s_and_saveexec_b64 s[14:15], vcc
	s_cbranch_execz .LBB0_218
	v_mov_b32_e32 v84, v19
	v_mov_b32_e32 v85, v51
	v_mov_b32_e32 v80, v18
	v_mov_b32_e32 v81, v50
	v_pk_mul_f32 v[84:85], v[84:85], v[84:85]
	v_pk_mul_f32 v[76:77], v[40:41], v[40:41]
	v_pk_fma_f32 v[80:81], v[80:81], v[80:81], v[84:85]
	v_mov_b32_e32 v84, v20
	v_mov_b32_e32 v85, v52
	v_pk_fma_f32 v[80:81], v[84:85], v[84:85], v[80:81]
	v_mov_b32_e32 v84, v21
	v_mov_b32_e32 v85, v53
	v_pk_fma_f32 v[80:81], v[84:85], v[84:85], v[80:81]
	v_mov_b32_e32 v84, v22
	v_mov_b32_e32 v85, v54
	v_pk_fma_f32 v[80:81], v[84:85], v[84:85], v[80:81]
	v_mov_b32_e32 v84, v23
	v_mov_b32_e32 v85, v55
	v_pk_fma_f32 v[80:81], v[84:85], v[84:85], v[80:81]
	v_mov_b32_e32 v84, v24
	v_mov_b32_e32 v85, v56
	v_pk_fma_f32 v[80:81], v[84:85], v[84:85], v[80:81]
	v_mov_b32_e32 v84, v25
	v_mov_b32_e32 v85, v57
	v_pk_fma_f32 v[80:81], v[84:85], v[84:85], v[80:81]
	v_mov_b32_e32 v84, v26
	v_mov_b32_e32 v85, v58
	v_pk_fma_f32 v[80:81], v[84:85], v[84:85], v[80:81]
	v_mov_b32_e32 v84, v27
	v_mov_b32_e32 v85, v59
	v_pk_fma_f32 v[80:81], v[84:85], v[84:85], v[80:81]
	v_mov_b32_e32 v84, v28
	v_mov_b32_e32 v85, v60
	v_pk_fma_f32 v[80:81], v[84:85], v[84:85], v[80:81]
	v_mov_b32_e32 v84, v29
	v_mov_b32_e32 v85, v61
	v_pk_fma_f32 v[80:81], v[84:85], v[84:85], v[80:81]
	v_mov_b32_e32 v84, v30
	v_mov_b32_e32 v85, v62
	v_pk_fma_f32 v[80:81], v[84:85], v[84:85], v[80:81]
	v_mov_b32_e32 v84, v31
	v_mov_b32_e32 v85, v63
	v_pk_fma_f32 v[80:81], v[84:85], v[84:85], v[80:81]
	v_mov_b32_e32 v84, v32
	v_mov_b32_e32 v85, v64
	v_pk_fma_f32 v[80:81], v[84:85], v[84:85], v[80:81]
	v_mov_b32_e32 v84, v33
	v_mov_b32_e32 v85, v65
	v_pk_fma_f32 v[80:81], v[84:85], v[84:85], v[80:81]
	v_mov_b32_e32 v84, v2
	v_mov_b32_e32 v85, v34
	v_pk_fma_f32 v[80:81], v[84:85], v[84:85], v[80:81]
	v_mov_b32_e32 v84, v3
	v_mov_b32_e32 v85, v35
	v_pk_fma_f32 v[80:81], v[84:85], v[84:85], v[80:81]
	v_mov_b32_e32 v84, v4
	v_mov_b32_e32 v85, v36
	v_pk_fma_f32 v[80:81], v[84:85], v[84:85], v[80:81]
	v_mov_b32_e32 v84, v5
	v_mov_b32_e32 v85, v37
	v_pk_fma_f32 v[80:81], v[84:85], v[84:85], v[80:81]
	v_mov_b32_e32 v84, v6
	v_mov_b32_e32 v85, v38
	v_pk_mul_f32 v[94:95], v[8:9], v[8:9]
	v_pk_fma_f32 v[80:81], v[84:85], v[84:85], v[80:81]
	v_mov_b32_e32 v84, v7
	v_mov_b32_e32 v85, v39
	v_pk_fma_f32 v[80:81], v[84:85], v[84:85], v[80:81]
	v_mov_b32_e32 v84, v94
	v_mov_b32_e32 v85, v76
	v_pk_mul_f32 v[74:75], v[42:43], v[42:43]
	v_pk_mul_f32 v[92:93], v[10:11], v[10:11]
	v_pk_add_f32 v[80:81], v[84:85], v[80:81]
	v_mov_b32_e32 v76, v95
	v_pk_add_f32 v[76:77], v[76:77], v[80:81]
	v_mov_b32_e32 v80, v92
	v_mov_b32_e32 v81, v74
	v_pk_mul_f32 v[72:73], v[44:45], v[44:45]
	v_pk_mul_f32 v[90:91], v[12:13], v[12:13]
	v_pk_add_f32 v[76:77], v[80:81], v[76:77]
	v_mov_b32_e32 v74, v93
	v_pk_add_f32 v[74:75], v[74:75], v[76:77]
	v_mov_b32_e32 v76, v90
	v_mov_b32_e32 v77, v72
	v_pk_mul_f32 v[70:71], v[46:47], v[46:47]
	v_pk_mul_f32 v[88:89], v[14:15], v[14:15]
	v_pk_add_f32 v[74:75], v[76:77], v[74:75]
	v_mov_b32_e32 v72, v91
	v_lshlrev_b32_e32 v0, 2, v130
	v_pk_add_f32 v[72:73], v[72:73], v[74:75]
	v_mov_b32_e32 v74, v88
	v_mov_b32_e32 v75, v70
	v_lshl_add_u64 v[78:79], v[66:67], 0, v[0:1]
	v_pk_mul_f32 v[66:67], v[48:49], v[48:49]
	v_pk_mul_f32 v[86:87], v[16:17], v[16:17]
	v_pk_add_f32 v[72:73], v[74:75], v[72:73]
	v_mov_b32_e32 v70, v89
	v_pk_add_f32 v[70:71], v[70:71], v[72:73]
	v_mov_b32_e32 v72, v86
	v_mov_b32_e32 v73, v66
	v_pk_add_f32 v[70:71], v[72:73], v[70:71]
	v_mov_b32_e32 v66, v87
	v_pk_add_f32 v[66:67], v[66:67], v[70:71]
	ds_bpermute_b32 v71, v154, v67
	ds_bpermute_b32 v70, v154, v66
	s_mov_b32 s0, 0x3c800000
	global_load_dwordx4 v[84:87], v[78:79], off offset:96
	global_load_dwordx4 v[156:159], v[78:79], off
	global_load_dwordx4 v[160:163], v[78:79], off offset:32
	global_load_dwordx4 v[164:167], v[78:79], off offset:64
	global_load_dwordx4 v[168:171], v[78:79], off offset:128
	global_load_dwordx4 v[172:175], v[78:79], off offset:160
	global_load_dwordx4 v[176:179], v[78:79], off offset:192
	global_load_dwordx4 v[180:183], v[78:79], off offset:224
	s_waitcnt lgkmcnt(0)
; DI void phase1(const Params& p, int l, char* lds) {
;     ...
;           ss += shx(ss, lane, 32);
;           const float rs = rsqrtf(ss * (1.f / 64.f) + 1e-6f) * sc;
; #pragma unroll
;           for (int ni = 0; ni < 2; ++ni)
; #pragma unroll
;             for (int i = 0; i < 16; ++i) acc[mi][ni][i] *= rs * gain[ni * 32 + (i & 3) + 8 * (i >> 2) + 4 * h];
;         }
	v_pk_add_f32 v[66:67], v[66:67], v[70:71]
	s_nop 0
	v_pk_fma_f32 v[66:67], v[66:67], s[0:1], v[222:223] op_sel_hi:[1,0,0]
	s_nop 0
	v_mul_f32_e32 v0, 0x4b800000, v67
	v_cmp_gt_f32_e64 s[0:1], s56, v67
	v_cmp_gt_f32_e32 vcc, s56, v66
	s_nop 0
	v_cndmask_b32_e64 v0, v67, v0, s[0:1]
	v_rsq_f32_e32 v0, v0
	s_nop 0
	v_mul_f32_e32 v67, 0x45800000, v0
	v_cndmask_b32_e64 v0, v0, v67, s[0:1]
	v_mul_f32_e32 v82, v68, v0
	v_mul_f32_e32 v0, 0x4b800000, v66
	v_cndmask_b32_e32 v0, v66, v0, vcc
	v_rsq_f32_e32 v0, v0
	s_nop 0
	v_mul_f32_e32 v66, 0x45800000, v0
	v_cndmask_b32_e32 v0, v0, v66, vcc
	v_mul_f32_e32 v0, v68, v0
	s_waitcnt vmcnt(6)
	v_pk_mul_f32 v[70:71], v[156:157], v[82:83] op_sel_hi:[1,0]
	s_nop 0
	v_pk_mul_f32 v[50:51], v[50:51], v[70:71]
	v_pk_mul_f32 v[70:71], v[158:159], v[82:83] op_sel_hi:[1,0]
	v_pk_mul_f32 v[66:67], v[156:157], v[0:1] op_sel_hi:[1,0]
	v_pk_mul_f32 v[52:53], v[52:53], v[70:71]
	v_pk_mul_f32 v[68:69], v[158:159], v[0:1] op_sel_hi:[1,0]
	v_pk_mul_f32 v[18:19], v[18:19], v[66:67]
	v_pk_mul_f32 v[20:21], v[20:21], v[68:69]
	s_waitcnt vmcnt(5)
	v_pk_mul_f32 v[74:75], v[160:161], v[82:83] op_sel_hi:[1,0]
	s_nop 0
	v_pk_mul_f32 v[54:55], v[54:55], v[74:75]
	v_pk_mul_f32 v[74:75], v[162:163], v[82:83] op_sel_hi:[1,0]
	v_pk_mul_f32 v[70:71], v[160:161], v[0:1] op_sel_hi:[1,0]
	v_pk_mul_f32 v[56:57], v[56:57], v[74:75]
	v_pk_mul_f32 v[72:73], v[162:163], v[0:1] op_sel_hi:[1,0]
	v_pk_mul_f32 v[22:23], v[22:23], v[70:71]
	v_pk_mul_f32 v[24:25], v[24:25], v[72:73]
	s_waitcnt vmcnt(4)
	v_pk_mul_f32 v[80:81], v[164:165], v[82:83] op_sel_hi:[1,0]
	s_nop 0
	v_pk_mul_f32 v[58:59], v[58:59], v[80:81]
	v_pk_mul_f32 v[80:81], v[82:83], v[166:167] op_sel_hi:[0,1]
	v_pk_mul_f32 v[60:61], v[60:61], v[80:81]
	v_pk_mul_f32 v[80:81], v[82:83], v[84:85] op_sel_hi:[0,1]
	v_pk_mul_f32 v[62:63], v[62:63], v[80:81]
	v_pk_mul_f32 v[80:81], v[82:83], v[86:87] op_sel_hi:[0,1]
	v_pk_mul_f32 v[64:65], v[64:65], v[80:81]
	v_pk_mul_f32 v[74:75], v[164:165], v[0:1] op_sel_hi:[1,0]
	v_pk_mul_f32 v[76:77], v[166:167], v[0:1] op_sel_hi:[1,0]
	v_pk_mul_f32 v[80:81], v[84:85], v[0:1] op_sel_hi:[1,0]
	v_pk_mul_f32 v[28:29], v[28:29], v[76:77]
	v_pk_mul_f32 v[30:31], v[30:31], v[80:81]
	v_pk_mul_f32 v[26:27], v[26:27], v[74:75]
	s_nop 0
	v_pk_mul_f32 v[84:85], v[86:87], v[0:1] op_sel_hi:[1,0]
	s_waitcnt vmcnt(3)
	v_pk_mul_f32 v[86:87], v[82:83], v[170:171] op_sel_hi:[0,1]
	v_pk_mul_f32 v[32:33], v[32:33], v[84:85]
	v_pk_mul_f32 v[84:85], v[82:83], v[168:169] op_sel_hi:[0,1]
	s_waitcnt vmcnt(2)
	v_pk_mul_f32 v[88:89], v[82:83], v[172:173] op_sel_hi:[0,1]
	v_pk_mul_f32 v[90:91], v[82:83], v[174:175] op_sel_hi:[0,1]
	s_waitcnt vmcnt(1)
	v_pk_mul_f32 v[92:93], v[82:83], v[176:177] op_sel_hi:[0,1]
	v_pk_mul_f32 v[94:95], v[82:83], v[178:179] op_sel_hi:[0,1]
	s_waitcnt vmcnt(0)
	v_pk_mul_f32 v[96:97], v[82:83], v[180:181] op_sel_hi:[0,1]
	v_pk_mul_f32 v[98:99], v[82:83], v[182:183] op_sel_hi:[0,1]
	v_pk_mul_f32 v[66:67], v[168:169], v[0:1] op_sel_hi:[1,0]
	v_pk_mul_f32 v[68:69], v[170:171], v[0:1] op_sel_hi:[1,0]
	v_pk_mul_f32 v[70:71], v[172:173], v[0:1] op_sel_hi:[1,0]
	v_pk_mul_f32 v[72:73], v[174:175], v[0:1] op_sel_hi:[1,0]
	v_pk_mul_f32 v[74:75], v[176:177], v[0:1] op_sel_hi:[1,0]
	v_pk_mul_f32 v[76:77], v[178:179], v[0:1] op_sel_hi:[1,0]
	v_pk_mul_f32 v[78:79], v[180:181], v[0:1] op_sel_hi:[1,0]
	v_pk_mul_f32 v[80:81], v[182:183], v[0:1] op_sel_hi:[1,0]
	v_pk_mul_f32 v[48:49], v[48:49], v[98:99]
	v_pk_mul_f32 v[46:47], v[46:47], v[96:97]
	v_pk_mul_f32 v[44:45], v[44:45], v[94:95]
	v_pk_mul_f32 v[42:43], v[42:43], v[92:93]
	v_pk_mul_f32 v[40:41], v[40:41], v[90:91]
	v_pk_mul_f32 v[38:39], v[38:39], v[88:89]
	v_pk_mul_f32 v[36:37], v[36:37], v[86:87]
	v_pk_mul_f32 v[34:35], v[34:35], v[84:85]
	v_pk_mul_f32 v[16:17], v[16:17], v[80:81]
	v_pk_mul_f32 v[14:15], v[14:15], v[78:79]
	v_pk_mul_f32 v[12:13], v[12:13], v[76:77]
	v_pk_mul_f32 v[10:11], v[10:11], v[74:75]
	v_pk_mul_f32 v[8:9], v[8:9], v[72:73]
	v_pk_mul_f32 v[6:7], v[6:7], v[70:71]
	v_pk_mul_f32 v[4:5], v[4:5], v[68:69]
	v_pk_mul_f32 v[2:3], v[2:3], v[66:67]
	s_branch .LBB0_218
